# v108 + attention loop second half: four prefetch-skip branches test SCC from one s_andn2 (4 SALU fewer per KV block)
# speedup vs baseline: 1.0020x; 1.0020x over previous
.LBB0_315:
	s_waitcnt lgkmcnt(14)
	v_mfma_f32_32x32x16_bf16 v[16:31], v[144:147], v[196:199], v[16:31]
	v_exp_f32_e32 v48, v48
	v_exp_f32_e32 v49, v49
	v_exp_f32_e32 v50, v50
	v_exp_f32_e32 v51, v51
	s_waitcnt lgkmcnt(12)
	v_mfma_f32_32x32x16_bf16 v[0:15], v[144:147], v[192:195], v[0:15]
	v_exp_f32_e32 v52, v52
	v_exp_f32_e32 v53, v53
	v_exp_f32_e32 v54, v54
	v_exp_f32_e32 v55, v55
	s_andn2_b64 s[8:9], exec, s[66:67]
	v_add_u32_e32 v72, s43, v238
	s_cbranch_scc1 .LBB0_317
	ds_read_b128 v[184:187], v72
	ds_read_b128 v[176:179], v72 offset:512
	v_add_u32_e32 v73, v239, v247
	v_add_u32_e32 v74, v239, v248
	ds_read_b128 v[152:155], v73
	ds_read_b128 v[148:151], v74
.LBB0_317:
	s_waitcnt lgkmcnt(10)
	v_mfma_f32_32x32x16_bf16 v[16:31], v[140:143], v[188:191], v[16:31]
	v_exp_f32_e32 v56, v56
	v_exp_f32_e32 v57, v57
	v_exp_f32_e32 v58, v58
	v_exp_f32_e32 v59, v59
	s_cbranch_scc1 .LBB0_319
	ds_read_b128 v[180:183], v72 offset:2048
	ds_read_b128 v[172:175], v72 offset:2560
.LBB0_319:
	s_waitcnt lgkmcnt(8)
	v_mfma_f32_32x32x16_bf16 v[0:15], v[140:143], v[88:91], v[0:15]
	v_exp_f32_e32 v60, v60
	v_exp_f32_e32 v61, v61
	v_exp_f32_e32 v62, v62
	v_exp_f32_e32 v63, v63
	s_cbranch_scc1 .LBB0_321
	ds_read_b128 v[168:171], v72 offset:4096
	ds_read_b128 v[164:167], v72 offset:4608
.LBB0_321:
	s_waitcnt lgkmcnt(6)
	v_mfma_f32_32x32x16_bf16 v[16:31], v[136:139], v[84:87], v[16:31]
	v_exp_f32_e32 v32, v32
	v_exp_f32_e32 v33, v33
	v_exp_f32_e32 v34, v34
	v_exp_f32_e32 v35, v35
	s_cbranch_scc1 .LBB0_323
	ds_read_b128 v[160:163], v72 offset:6144
	ds_read_b128 v[156:159], v72 offset:6656
